# hand-written ConvFFN (UP) epilogue body: DPP row rotations instead of ds_bpermute, 8-element stage interleave, no operand-shuffle movs; same arithmetic order
# speedup vs baseline: 1.0085x; 1.0085x over previous
.LBB0_326:
	s_or_b64 exec, exec, s[0:1]
	v_lshl_add_u64 v[130:131], v[182:183], 2, s[30:31]
	v_lshl_add_u64 v[138:139], v[186:187], 2, v[130:131]
	s_mov_b64 s[0:1], 0x2c00
	v_add_co_u32_e32 v136, vcc, 0x2000, v138
	v_lshl_add_u64 v[134:135], v[138:139], 0, s[0:1]
	s_nop 0
	v_addc_co_u32_e32 v137, vcc, 0, v139, vcc
	s_mov_b64 s[0:1], 0x5800
	s_waitcnt lgkmcnt(0)
	s_waitcnt vmcnt(0) lgkmcnt(0)
	s_barrier
	global_load_dwordx4 v[130:133], v[138:139], off offset:16
	global_load_dwordx4 v[142:145], v[138:139], off
	v_lshl_add_u64 v[140:141], v[138:139], 0, s[0:1]
	v_add_co_u32_e32 v138, vcc, 0x5000, v138
	global_load_dwordx4 v[146:149], v[136:137], off offset:3072
	s_nop 0
	global_load_dwordx4 v[134:137], v[134:135], off offset:16
	v_addc_co_u32_e32 v139, vcc, 0, v139, vcc
	global_load_dwordx4 v[150:153], v[138:139], off offset:2048
	s_nop 0
	global_load_dwordx4 v[138:141], v[140:141], off offset:16
	s_and_b64 s[0:1], s[2:3], exec
	s_cselect_b32 s53, s65, s53
	s_cselect_b32 s52, s64, s52
	v_lshl_add_u32 v0, v186, 2, s67
	v_lshl_add_u32 v228, v186, 2, s66
	s_andn2_b64 vcc, exec, s[38:39]
	s_cbranch_vccnz .Lffn_z0
	ds_read_b128 v[200:203], v0
	ds_read_b128 v[192:195], v0 offset:512
	ds_read_b128 v[204:207], v0 offset:16
	ds_read_b128 v[196:199], v0 offset:528
	s_branch .Lffn_d0
.Lffn_z0:
	v_mov_b32_e32 v192, 0
	v_mov_b32_e32 v193, 0
	v_mov_b32_e32 v194, 0
	v_mov_b32_e32 v195, 0
	v_mov_b32_e32 v196, 0
	v_mov_b32_e32 v197, 0
	v_mov_b32_e32 v198, 0
	v_mov_b32_e32 v199, 0
	v_mov_b32_e32 v200, 0
	v_mov_b32_e32 v201, 0
	v_mov_b32_e32 v202, 0
	v_mov_b32_e32 v203, 0
	v_mov_b32_e32 v204, 0
	v_mov_b32_e32 v205, 0
	v_mov_b32_e32 v206, 0
	v_mov_b32_e32 v207, 0
.Lffn_d0:
	v_add_u32_e32 v230, s41, v184
	s_lshl_b32 s6, s54, 8
	v_add_u32_e32 v230, s6, v230
	v_mov_b64_e32 v[158:159], s[52:53]
	s_movk_i32 s6, 0x1600
	v_mad_i64_i32 v[158:159], s[8:9], v230, s6, v[158:159]
	v_lshl_add_u64 v[158:159], v[182:183], 1, v[158:159]
	v_lshl_add_u64 v[158:159], v[186:187], 1, v[158:159]
	s_mov_b32 s6, 0x16000
	s_mov_b32 s7, 0
	v_cmp_eq_u32_e64 s[4:5], 0, v184
	v_cmp_lt_i32_e64 s[0:1], 0, v184
	v_cmp_lt_i32_e64 s[8:9], 1, v184
	s_waitcnt vmcnt(0) lgkmcnt(0)
	v_cndmask_b32_e64 v200, v192, v200, s[4:5]
	v_cndmask_b32_e64 v201, v193, v201, s[4:5]
	v_cndmask_b32_e64 v202, v194, v202, s[4:5]
	v_cndmask_b32_e64 v203, v195, v203, s[4:5]
	v_cndmask_b32_e64 v204, v196, v204, s[4:5]
	v_cndmask_b32_e64 v205, v197, v205, s[4:5]
	v_cndmask_b32_e64 v206, v198, v206, s[4:5]
	v_cndmask_b32_e64 v207, v199, v207, s[4:5]
	v_mov_b32_dpp v208, v126 row_ror:1 row_mask:0xf bank_mask:0xf
	v_mov_b32_dpp v209, v127 row_ror:1 row_mask:0xf bank_mask:0xf
	v_mov_b32_dpp v210, v128 row_ror:1 row_mask:0xf bank_mask:0xf
	v_mov_b32_dpp v211, v129 row_ror:1 row_mask:0xf bank_mask:0xf
	v_mov_b32_dpp v212, v122 row_ror:1 row_mask:0xf bank_mask:0xf
	v_mov_b32_dpp v213, v123 row_ror:1 row_mask:0xf bank_mask:0xf
	v_mov_b32_dpp v214, v124 row_ror:1 row_mask:0xf bank_mask:0xf
	v_mov_b32_dpp v215, v125 row_ror:1 row_mask:0xf bank_mask:0xf
	v_mov_b32_dpp v160, v126 row_ror:2 row_mask:0xf bank_mask:0xf
	v_mov_b32_dpp v161, v127 row_ror:2 row_mask:0xf bank_mask:0xf
	v_mov_b32_dpp v162, v128 row_ror:2 row_mask:0xf bank_mask:0xf
	v_mov_b32_dpp v163, v129 row_ror:2 row_mask:0xf bank_mask:0xf
	v_mov_b32_dpp v164, v122 row_ror:2 row_mask:0xf bank_mask:0xf
	v_mov_b32_dpp v165, v123 row_ror:2 row_mask:0xf bank_mask:0xf
	v_mov_b32_dpp v166, v124 row_ror:2 row_mask:0xf bank_mask:0xf
	v_mov_b32_dpp v167, v125 row_ror:2 row_mask:0xf bank_mask:0xf
	v_cndmask_b32_e64 v192, v192, v208, s[0:1]
	v_cndmask_b32_e64 v193, v193, v209, s[0:1]
	v_cndmask_b32_e64 v194, v194, v210, s[0:1]
	v_cndmask_b32_e64 v195, v195, v211, s[0:1]
	v_cndmask_b32_e64 v196, v196, v212, s[0:1]
	v_cndmask_b32_e64 v197, v197, v213, s[0:1]
	v_cndmask_b32_e64 v198, v198, v214, s[0:1]
	v_cndmask_b32_e64 v199, v199, v215, s[0:1]
	v_cndmask_b32_e64 v200, v200, v160, s[8:9]
	v_cndmask_b32_e64 v201, v201, v161, s[8:9]
	v_cndmask_b32_e64 v202, v202, v162, s[8:9]
	v_cndmask_b32_e64 v203, v203, v163, s[8:9]
	v_cndmask_b32_e64 v204, v204, v164, s[8:9]
	v_cndmask_b32_e64 v205, v205, v165, s[8:9]
	v_cndmask_b32_e64 v206, v206, v166, s[8:9]
	v_cndmask_b32_e64 v207, v207, v167, s[8:9]
	v_mul_f32_e32 v192, v146, v192
	v_mul_f32_e32 v193, v147, v193
	v_mul_f32_e32 v194, v148, v194
	v_mul_f32_e32 v195, v149, v195
	v_mul_f32_e32 v196, v134, v196
	v_mul_f32_e32 v197, v135, v197
	v_mul_f32_e32 v198, v136, v198
	v_mul_f32_e32 v199, v137, v199
	v_mul_f32_e32 v168, v126, v150
	v_mul_f32_e32 v169, v127, v151
	v_mul_f32_e32 v182, v128, v152
	v_mul_f32_e32 v183, v129, v153
	v_mul_f32_e32 v184, v122, v138
	v_mul_f32_e32 v185, v123, v139
	v_mul_f32_e32 v186, v124, v140
	v_mul_f32_e32 v187, v125, v141
	v_fma_f32 v200, v142, v200, v192
	v_fma_f32 v201, v143, v201, v193
	v_fma_f32 v202, v144, v202, v194
	v_fma_f32 v203, v145, v203, v195
	v_fma_f32 v204, v130, v204, v196
	v_fma_f32 v205, v131, v205, v197
	v_fma_f32 v206, v132, v206, v198
	v_fma_f32 v207, v133, v207, v199
	v_add_f32_e32 v168, v168, v200
	v_add_f32_e32 v169, v169, v201
	v_add_f32_e32 v182, v182, v202
	v_add_f32_e32 v183, v183, v203
	v_add_f32_e32 v184, v184, v204
	v_add_f32_e32 v185, v185, v205
	v_add_f32_e32 v186, v186, v206
	v_add_f32_e32 v187, v187, v207
	v_mul_f32_e32 v200, 0xbfb8aa3b, v168
	v_mul_f32_e32 v201, 0xbfb8aa3b, v169
	v_mul_f32_e32 v202, 0xbfb8aa3b, v182
	v_mul_f32_e32 v203, 0xbfb8aa3b, v183
	v_mul_f32_e32 v204, 0xbfb8aa3b, v184
	v_mul_f32_e32 v205, 0xbfb8aa3b, v185
	v_mul_f32_e32 v206, 0xbfb8aa3b, v186
	v_mul_f32_e32 v207, 0xbfb8aa3b, v187
	v_exp_f32_e32 v200, v200
	v_exp_f32_e32 v201, v201
	v_exp_f32_e32 v202, v202
	v_exp_f32_e32 v203, v203
	v_exp_f32_e32 v204, v204
	v_exp_f32_e32 v205, v205
	v_exp_f32_e32 v206, v206
	v_exp_f32_e32 v207, v207
	v_add_f32_e32 v200, 1.0, v200
	v_add_f32_e32 v201, 1.0, v201
	v_add_f32_e32 v202, 1.0, v202
	v_add_f32_e32 v203, 1.0, v203
	v_add_f32_e32 v204, 1.0, v204
	v_add_f32_e32 v205, 1.0, v205
	v_add_f32_e32 v206, 1.0, v206
	v_add_f32_e32 v207, 1.0, v207
	v_rcp_f32_e32 v200, v200
	v_rcp_f32_e32 v201, v201
	v_rcp_f32_e32 v202, v202
	v_rcp_f32_e32 v203, v203
	v_rcp_f32_e32 v204, v204
	v_rcp_f32_e32 v205, v205
	v_rcp_f32_e32 v206, v206
	v_rcp_f32_e32 v207, v207
	v_mul_f32_e32 v168, v168, v200
	v_mul_f32_e32 v169, v169, v201
	v_mul_f32_e32 v182, v182, v202
	v_mul_f32_e32 v183, v183, v203
	v_mul_f32_e32 v184, v184, v204
	v_mul_f32_e32 v185, v185, v205
	v_mul_f32_e32 v186, v186, v206
	v_mul_f32_e32 v187, v187, v207
	v_mul_f32_e32 v168, v94, v168
	v_mul_f32_e32 v169, v95, v169
	v_mul_f32_e32 v182, v96, v182
	v_mul_f32_e32 v183, v97, v183
	v_mul_f32_e32 v184, v90, v184
	v_mul_f32_e32 v185, v91, v185
	v_mul_f32_e32 v186, v92, v186
	v_mul_f32_e32 v187, v93, v187
	v_cvt_pk_bf16_f32 v154, v168, v169
	v_cvt_pk_bf16_f32 v155, v182, v183
	v_cvt_pk_bf16_f32 v156, v184, v185
	v_cvt_pk_bf16_f32 v157, v186, v187
	flat_store_dwordx4 v[158:159], v[154:157]
	v_lshl_add_u64 v[158:159], v[158:159], 0, s[6:7]
	v_mov_b32_dpp v192, v118 row_ror:1 row_mask:0xf bank_mask:0xf
	v_mov_b32_dpp v193, v119 row_ror:1 row_mask:0xf bank_mask:0xf
	v_mov_b32_dpp v194, v120 row_ror:1 row_mask:0xf bank_mask:0xf
	v_mov_b32_dpp v195, v121 row_ror:1 row_mask:0xf bank_mask:0xf
	v_mov_b32_dpp v196, v114 row_ror:1 row_mask:0xf bank_mask:0xf
	v_mov_b32_dpp v197, v115 row_ror:1 row_mask:0xf bank_mask:0xf
	v_mov_b32_dpp v198, v116 row_ror:1 row_mask:0xf bank_mask:0xf
	v_mov_b32_dpp v199, v117 row_ror:1 row_mask:0xf bank_mask:0xf
	v_mov_b32_dpp v200, v118 row_ror:2 row_mask:0xf bank_mask:0xf
	v_mov_b32_dpp v201, v119 row_ror:2 row_mask:0xf bank_mask:0xf
	v_mov_b32_dpp v202, v120 row_ror:2 row_mask:0xf bank_mask:0xf
	v_mov_b32_dpp v203, v121 row_ror:2 row_mask:0xf bank_mask:0xf
	v_mov_b32_dpp v204, v114 row_ror:2 row_mask:0xf bank_mask:0xf
	v_mov_b32_dpp v205, v115 row_ror:2 row_mask:0xf bank_mask:0xf
	v_mov_b32_dpp v206, v116 row_ror:2 row_mask:0xf bank_mask:0xf
	v_mov_b32_dpp v207, v117 row_ror:2 row_mask:0xf bank_mask:0xf
	v_cndmask_b32_e64 v208, v208, v192, s[0:1]
	v_cndmask_b32_e64 v209, v209, v193, s[0:1]
	v_cndmask_b32_e64 v210, v210, v194, s[0:1]
	v_cndmask_b32_e64 v211, v211, v195, s[0:1]
	v_cndmask_b32_e64 v212, v212, v196, s[0:1]
	v_cndmask_b32_e64 v213, v213, v197, s[0:1]
	v_cndmask_b32_e64 v214, v214, v198, s[0:1]
	v_cndmask_b32_e64 v215, v215, v199, s[0:1]
	v_cndmask_b32_e64 v160, v160, v200, s[8:9]
	v_cndmask_b32_e64 v161, v161, v201, s[8:9]
	v_cndmask_b32_e64 v162, v162, v202, s[8:9]
	v_cndmask_b32_e64 v163, v163, v203, s[8:9]
	v_cndmask_b32_e64 v164, v164, v204, s[8:9]
	v_cndmask_b32_e64 v165, v165, v205, s[8:9]
	v_cndmask_b32_e64 v166, v166, v206, s[8:9]
	v_cndmask_b32_e64 v167, v167, v207, s[8:9]
	v_mul_f32_e32 v208, v146, v208
	v_mul_f32_e32 v209, v147, v209
	v_mul_f32_e32 v210, v148, v210
	v_mul_f32_e32 v211, v149, v211
	v_mul_f32_e32 v212, v134, v212
	v_mul_f32_e32 v213, v135, v213
	v_mul_f32_e32 v214, v136, v214
	v_mul_f32_e32 v215, v137, v215
	v_mul_f32_e32 v168, v118, v150
	v_mul_f32_e32 v169, v119, v151
	v_mul_f32_e32 v182, v120, v152
	v_mul_f32_e32 v183, v121, v153
	v_mul_f32_e32 v184, v114, v138
	v_mul_f32_e32 v185, v115, v139
	v_mul_f32_e32 v186, v116, v140
	v_mul_f32_e32 v187, v117, v141
	v_fma_f32 v160, v142, v160, v208
	v_fma_f32 v161, v143, v161, v209
	v_fma_f32 v162, v144, v162, v210
	v_fma_f32 v163, v145, v163, v211
	v_fma_f32 v164, v130, v164, v212
	v_fma_f32 v165, v131, v165, v213
	v_fma_f32 v166, v132, v166, v214
	v_fma_f32 v167, v133, v167, v215
	v_add_f32_e32 v168, v168, v160
	v_add_f32_e32 v169, v169, v161
	v_add_f32_e32 v182, v182, v162
	v_add_f32_e32 v183, v183, v163
	v_add_f32_e32 v184, v184, v164
	v_add_f32_e32 v185, v185, v165
	v_add_f32_e32 v186, v186, v166
	v_add_f32_e32 v187, v187, v167
	v_mul_f32_e32 v160, 0xbfb8aa3b, v168
	v_mul_f32_e32 v161, 0xbfb8aa3b, v169
	v_mul_f32_e32 v162, 0xbfb8aa3b, v182
	v_mul_f32_e32 v163, 0xbfb8aa3b, v183
	v_mul_f32_e32 v164, 0xbfb8aa3b, v184
	v_mul_f32_e32 v165, 0xbfb8aa3b, v185
	v_mul_f32_e32 v166, 0xbfb8aa3b, v186
	v_mul_f32_e32 v167, 0xbfb8aa3b, v187
	v_exp_f32_e32 v160, v160
	v_exp_f32_e32 v161, v161
	v_exp_f32_e32 v162, v162
	v_exp_f32_e32 v163, v163
	v_exp_f32_e32 v164, v164
	v_exp_f32_e32 v165, v165
	v_exp_f32_e32 v166, v166
	v_exp_f32_e32 v167, v167
	v_add_f32_e32 v160, 1.0, v160
	v_add_f32_e32 v161, 1.0, v161
	v_add_f32_e32 v162, 1.0, v162
	v_add_f32_e32 v163, 1.0, v163
	v_add_f32_e32 v164, 1.0, v164
	v_add_f32_e32 v165, 1.0, v165
	v_add_f32_e32 v166, 1.0, v166
	v_add_f32_e32 v167, 1.0, v167
	v_rcp_f32_e32 v160, v160
	v_rcp_f32_e32 v161, v161
	v_rcp_f32_e32 v162, v162
	v_rcp_f32_e32 v163, v163
	v_rcp_f32_e32 v164, v164
	v_rcp_f32_e32 v165, v165
	v_rcp_f32_e32 v166, v166
	v_rcp_f32_e32 v167, v167
	v_mul_f32_e32 v168, v168, v160
	v_mul_f32_e32 v169, v169, v161
	v_mul_f32_e32 v182, v182, v162
	v_mul_f32_e32 v183, v183, v163
	v_mul_f32_e32 v184, v184, v164
	v_mul_f32_e32 v185, v185, v165
	v_mul_f32_e32 v186, v186, v166
	v_mul_f32_e32 v187, v187, v167
	v_mul_f32_e32 v168, v86, v168
	v_mul_f32_e32 v169, v87, v169
	v_mul_f32_e32 v182, v88, v182
	v_mul_f32_e32 v183, v89, v183
	v_mul_f32_e32 v184, v82, v184
	v_mul_f32_e32 v185, v83, v185
	v_mul_f32_e32 v186, v84, v186
	v_mul_f32_e32 v187, v85, v187
	v_cvt_pk_bf16_f32 v154, v168, v169
	v_cvt_pk_bf16_f32 v155, v182, v183
	v_cvt_pk_bf16_f32 v156, v184, v185
	v_cvt_pk_bf16_f32 v157, v186, v187
	flat_store_dwordx4 v[158:159], v[154:157]
	v_lshl_add_u64 v[158:159], v[158:159], 0, s[6:7]
	v_mov_b32_dpp v208, v110 row_ror:1 row_mask:0xf bank_mask:0xf
	v_mov_b32_dpp v209, v111 row_ror:1 row_mask:0xf bank_mask:0xf
	v_mov_b32_dpp v210, v112 row_ror:1 row_mask:0xf bank_mask:0xf
	v_mov_b32_dpp v211, v113 row_ror:1 row_mask:0xf bank_mask:0xf
	v_mov_b32_dpp v212, v106 row_ror:1 row_mask:0xf bank_mask:0xf
	v_mov_b32_dpp v213, v107 row_ror:1 row_mask:0xf bank_mask:0xf
	v_mov_b32_dpp v214, v108 row_ror:1 row_mask:0xf bank_mask:0xf
	v_mov_b32_dpp v215, v109 row_ror:1 row_mask:0xf bank_mask:0xf
	v_mov_b32_dpp v160, v110 row_ror:2 row_mask:0xf bank_mask:0xf
	v_mov_b32_dpp v161, v111 row_ror:2 row_mask:0xf bank_mask:0xf
	v_mov_b32_dpp v162, v112 row_ror:2 row_mask:0xf bank_mask:0xf
	v_mov_b32_dpp v163, v113 row_ror:2 row_mask:0xf bank_mask:0xf
	v_mov_b32_dpp v164, v106 row_ror:2 row_mask:0xf bank_mask:0xf
	v_mov_b32_dpp v165, v107 row_ror:2 row_mask:0xf bank_mask:0xf
	v_mov_b32_dpp v166, v108 row_ror:2 row_mask:0xf bank_mask:0xf
	v_mov_b32_dpp v167, v109 row_ror:2 row_mask:0xf bank_mask:0xf
	v_cndmask_b32_e64 v192, v192, v208, s[0:1]
	v_cndmask_b32_e64 v193, v193, v209, s[0:1]
	v_cndmask_b32_e64 v194, v194, v210, s[0:1]
	v_cndmask_b32_e64 v195, v195, v211, s[0:1]
	v_cndmask_b32_e64 v196, v196, v212, s[0:1]
	v_cndmask_b32_e64 v197, v197, v213, s[0:1]
	v_cndmask_b32_e64 v198, v198, v214, s[0:1]
	v_cndmask_b32_e64 v199, v199, v215, s[0:1]
	v_cndmask_b32_e64 v200, v200, v160, s[8:9]
	v_cndmask_b32_e64 v201, v201, v161, s[8:9]
	v_cndmask_b32_e64 v202, v202, v162, s[8:9]
	v_cndmask_b32_e64 v203, v203, v163, s[8:9]
	v_cndmask_b32_e64 v204, v204, v164, s[8:9]
	v_cndmask_b32_e64 v205, v205, v165, s[8:9]
	v_cndmask_b32_e64 v206, v206, v166, s[8:9]
	v_cndmask_b32_e64 v207, v207, v167, s[8:9]
	v_mul_f32_e32 v192, v146, v192
	v_mul_f32_e32 v193, v147, v193
	v_mul_f32_e32 v194, v148, v194
	v_mul_f32_e32 v195, v149, v195
	v_mul_f32_e32 v196, v134, v196
	v_mul_f32_e32 v197, v135, v197
	v_mul_f32_e32 v198, v136, v198
	v_mul_f32_e32 v199, v137, v199
	v_mul_f32_e32 v168, v110, v150
	v_mul_f32_e32 v169, v111, v151
	v_mul_f32_e32 v182, v112, v152
	v_mul_f32_e32 v183, v113, v153
	v_mul_f32_e32 v184, v106, v138
	v_mul_f32_e32 v185, v107, v139
	v_mul_f32_e32 v186, v108, v140
	v_mul_f32_e32 v187, v109, v141
	v_fma_f32 v200, v142, v200, v192
	v_fma_f32 v201, v143, v201, v193
	v_fma_f32 v202, v144, v202, v194
	v_fma_f32 v203, v145, v203, v195
	v_fma_f32 v204, v130, v204, v196
	v_fma_f32 v205, v131, v205, v197
	v_fma_f32 v206, v132, v206, v198
	v_fma_f32 v207, v133, v207, v199
	v_add_f32_e32 v168, v168, v200
	v_add_f32_e32 v169, v169, v201
	v_add_f32_e32 v182, v182, v202
	v_add_f32_e32 v183, v183, v203
	v_add_f32_e32 v184, v184, v204
	v_add_f32_e32 v185, v185, v205
	v_add_f32_e32 v186, v186, v206
	v_add_f32_e32 v187, v187, v207
	v_mul_f32_e32 v200, 0xbfb8aa3b, v168
	v_mul_f32_e32 v201, 0xbfb8aa3b, v169
	v_mul_f32_e32 v202, 0xbfb8aa3b, v182
	v_mul_f32_e32 v203, 0xbfb8aa3b, v183
	v_mul_f32_e32 v204, 0xbfb8aa3b, v184
	v_mul_f32_e32 v205, 0xbfb8aa3b, v185
	v_mul_f32_e32 v206, 0xbfb8aa3b, v186
	v_mul_f32_e32 v207, 0xbfb8aa3b, v187
	v_exp_f32_e32 v200, v200
	v_exp_f32_e32 v201, v201
	v_exp_f32_e32 v202, v202
	v_exp_f32_e32 v203, v203
	v_exp_f32_e32 v204, v204
	v_exp_f32_e32 v205, v205
	v_exp_f32_e32 v206, v206
	v_exp_f32_e32 v207, v207
	v_add_f32_e32 v200, 1.0, v200
	v_add_f32_e32 v201, 1.0, v201
	v_add_f32_e32 v202, 1.0, v202
	v_add_f32_e32 v203, 1.0, v203
	v_add_f32_e32 v204, 1.0, v204
	v_add_f32_e32 v205, 1.0, v205
	v_add_f32_e32 v206, 1.0, v206
	v_add_f32_e32 v207, 1.0, v207
	v_rcp_f32_e32 v200, v200
	v_rcp_f32_e32 v201, v201
	v_rcp_f32_e32 v202, v202
	v_rcp_f32_e32 v203, v203
	v_rcp_f32_e32 v204, v204
	v_rcp_f32_e32 v205, v205
	v_rcp_f32_e32 v206, v206
	v_rcp_f32_e32 v207, v207
	v_mul_f32_e32 v168, v168, v200
	v_mul_f32_e32 v169, v169, v201
	v_mul_f32_e32 v182, v182, v202
	v_mul_f32_e32 v183, v183, v203
	v_mul_f32_e32 v184, v184, v204
	v_mul_f32_e32 v185, v185, v205
	v_mul_f32_e32 v186, v186, v206
	v_mul_f32_e32 v187, v187, v207
	v_mul_f32_e32 v168, v78, v168
	v_mul_f32_e32 v169, v79, v169
	v_mul_f32_e32 v182, v80, v182
	v_mul_f32_e32 v183, v81, v183
	v_mul_f32_e32 v184, v74, v184
	v_mul_f32_e32 v185, v75, v185
	v_mul_f32_e32 v186, v76, v186
	v_mul_f32_e32 v187, v77, v187
	v_cvt_pk_bf16_f32 v154, v168, v169
	v_cvt_pk_bf16_f32 v155, v182, v183
	v_cvt_pk_bf16_f32 v156, v184, v185
	v_cvt_pk_bf16_f32 v157, v186, v187
	flat_store_dwordx4 v[158:159], v[154:157]
	v_lshl_add_u64 v[158:159], v[158:159], 0, s[6:7]
	v_mov_b32_dpp v192, v102 row_ror:1 row_mask:0xf bank_mask:0xf
	v_mov_b32_dpp v193, v103 row_ror:1 row_mask:0xf bank_mask:0xf
	v_mov_b32_dpp v194, v104 row_ror:1 row_mask:0xf bank_mask:0xf
	v_mov_b32_dpp v195, v105 row_ror:1 row_mask:0xf bank_mask:0xf
	v_mov_b32_dpp v196, v98 row_ror:1 row_mask:0xf bank_mask:0xf
	v_mov_b32_dpp v197, v99 row_ror:1 row_mask:0xf bank_mask:0xf
	v_mov_b32_dpp v198, v100 row_ror:1 row_mask:0xf bank_mask:0xf
	v_mov_b32_dpp v199, v101 row_ror:1 row_mask:0xf bank_mask:0xf
	v_mov_b32_dpp v200, v102 row_ror:2 row_mask:0xf bank_mask:0xf
	v_mov_b32_dpp v201, v103 row_ror:2 row_mask:0xf bank_mask:0xf
	v_mov_b32_dpp v202, v104 row_ror:2 row_mask:0xf bank_mask:0xf
	v_mov_b32_dpp v203, v105 row_ror:2 row_mask:0xf bank_mask:0xf
	v_mov_b32_dpp v204, v98 row_ror:2 row_mask:0xf bank_mask:0xf
	v_mov_b32_dpp v205, v99 row_ror:2 row_mask:0xf bank_mask:0xf
	v_mov_b32_dpp v206, v100 row_ror:2 row_mask:0xf bank_mask:0xf
	v_mov_b32_dpp v207, v101 row_ror:2 row_mask:0xf bank_mask:0xf
	v_cndmask_b32_e64 v208, v208, v192, s[0:1]
	v_cndmask_b32_e64 v209, v209, v193, s[0:1]
	v_cndmask_b32_e64 v210, v210, v194, s[0:1]
	v_cndmask_b32_e64 v211, v211, v195, s[0:1]
	v_cndmask_b32_e64 v212, v212, v196, s[0:1]
	v_cndmask_b32_e64 v213, v213, v197, s[0:1]
	v_cndmask_b32_e64 v214, v214, v198, s[0:1]
	v_cndmask_b32_e64 v215, v215, v199, s[0:1]
	v_cndmask_b32_e64 v160, v160, v200, s[8:9]
	v_cndmask_b32_e64 v161, v161, v201, s[8:9]
	v_cndmask_b32_e64 v162, v162, v202, s[8:9]
	v_cndmask_b32_e64 v163, v163, v203, s[8:9]
	v_cndmask_b32_e64 v164, v164, v204, s[8:9]
	v_cndmask_b32_e64 v165, v165, v205, s[8:9]
	v_cndmask_b32_e64 v166, v166, v206, s[8:9]
	v_cndmask_b32_e64 v167, v167, v207, s[8:9]
	v_mul_f32_e32 v208, v146, v208
	v_mul_f32_e32 v209, v147, v209
	v_mul_f32_e32 v210, v148, v210
	v_mul_f32_e32 v211, v149, v211
	v_mul_f32_e32 v212, v134, v212
	v_mul_f32_e32 v213, v135, v213
	v_mul_f32_e32 v214, v136, v214
	v_mul_f32_e32 v215, v137, v215
	v_mul_f32_e32 v168, v102, v150
	v_mul_f32_e32 v169, v103, v151
	v_mul_f32_e32 v182, v104, v152
	v_mul_f32_e32 v183, v105, v153
	v_mul_f32_e32 v184, v98, v138
	v_mul_f32_e32 v185, v99, v139
	v_mul_f32_e32 v186, v100, v140
	v_mul_f32_e32 v187, v101, v141
	v_fma_f32 v160, v142, v160, v208
	v_fma_f32 v161, v143, v161, v209
	v_fma_f32 v162, v144, v162, v210
	v_fma_f32 v163, v145, v163, v211
	v_fma_f32 v164, v130, v164, v212
	v_fma_f32 v165, v131, v165, v213
	v_fma_f32 v166, v132, v166, v214
	v_fma_f32 v167, v133, v167, v215
	v_add_f32_e32 v168, v168, v160
	v_add_f32_e32 v169, v169, v161
	v_add_f32_e32 v182, v182, v162
	v_add_f32_e32 v183, v183, v163
	v_add_f32_e32 v184, v184, v164
	v_add_f32_e32 v185, v185, v165
	v_add_f32_e32 v186, v186, v166
	v_add_f32_e32 v187, v187, v167
	v_mul_f32_e32 v160, 0xbfb8aa3b, v168
	v_mul_f32_e32 v161, 0xbfb8aa3b, v169
	v_mul_f32_e32 v162, 0xbfb8aa3b, v182
	v_mul_f32_e32 v163, 0xbfb8aa3b, v183
	v_mul_f32_e32 v164, 0xbfb8aa3b, v184
	v_mul_f32_e32 v165, 0xbfb8aa3b, v185
	v_mul_f32_e32 v166, 0xbfb8aa3b, v186
	v_mul_f32_e32 v167, 0xbfb8aa3b, v187
	v_exp_f32_e32 v160, v160
	v_exp_f32_e32 v161, v161
	v_exp_f32_e32 v162, v162
	v_exp_f32_e32 v163, v163
	v_exp_f32_e32 v164, v164
	v_exp_f32_e32 v165, v165
	v_exp_f32_e32 v166, v166
	v_exp_f32_e32 v167, v167
	v_add_f32_e32 v160, 1.0, v160
	v_add_f32_e32 v161, 1.0, v161
	v_add_f32_e32 v162, 1.0, v162
	v_add_f32_e32 v163, 1.0, v163
	v_add_f32_e32 v164, 1.0, v164
	v_add_f32_e32 v165, 1.0, v165
	v_add_f32_e32 v166, 1.0, v166
	v_add_f32_e32 v167, 1.0, v167
	v_rcp_f32_e32 v160, v160
	v_rcp_f32_e32 v161, v161
	v_rcp_f32_e32 v162, v162
	v_rcp_f32_e32 v163, v163
	v_rcp_f32_e32 v164, v164
	v_rcp_f32_e32 v165, v165
	v_rcp_f32_e32 v166, v166
	v_rcp_f32_e32 v167, v167
	v_mul_f32_e32 v168, v168, v160
	v_mul_f32_e32 v169, v169, v161
	v_mul_f32_e32 v182, v182, v162
	v_mul_f32_e32 v183, v183, v163
	v_mul_f32_e32 v184, v184, v164
	v_mul_f32_e32 v185, v185, v165
	v_mul_f32_e32 v186, v186, v166
	v_mul_f32_e32 v187, v187, v167
	v_mul_f32_e32 v168, v70, v168
	v_mul_f32_e32 v169, v71, v169
	v_mul_f32_e32 v182, v72, v182
	v_mul_f32_e32 v183, v73, v183
	v_mul_f32_e32 v184, v66, v184
	v_mul_f32_e32 v185, v67, v185
	v_mul_f32_e32 v186, v68, v186
	v_mul_f32_e32 v187, v69, v187
	v_cvt_pk_bf16_f32 v154, v168, v169
	v_cvt_pk_bf16_f32 v155, v182, v183
	v_cvt_pk_bf16_f32 v156, v184, v185
	v_cvt_pk_bf16_f32 v157, v186, v187
	flat_store_dwordx4 v[158:159], v[154:157]
	v_add_co_u32_e32 v158, vcc, 0x6e000, v158
	s_nop 1
	v_addc_co_u32_e32 v159, vcc, 0, v159, vcc
	s_andn2_b64 vcc, exec, s[46:47]
	s_cbranch_vccnz .Lffn_z1
	ds_read_b128 v[200:203], v228 offset:1024
	ds_read_b128 v[192:195], v228 offset:1536
	ds_read_b128 v[204:207], v228 offset:1040
	ds_read_b128 v[196:199], v228 offset:1552
	s_branch .Lffn_d1

.Lffn_d1:
	s_waitcnt lgkmcnt(0)
	v_cndmask_b32_e64 v200, v192, v200, s[4:5]
	v_cndmask_b32_e64 v201, v193, v201, s[4:5]
	v_cndmask_b32_e64 v202, v194, v202, s[4:5]
	v_cndmask_b32_e64 v203, v195, v203, s[4:5]
	v_cndmask_b32_e64 v204, v196, v204, s[4:5]
	v_cndmask_b32_e64 v205, v197, v205, s[4:5]
	v_cndmask_b32_e64 v206, v198, v206, s[4:5]
	v_cndmask_b32_e64 v207, v199, v207, s[4:5]
	v_mov_b32_dpp v208, v62 row_ror:1 row_mask:0xf bank_mask:0xf
	v_mov_b32_dpp v209, v63 row_ror:1 row_mask:0xf bank_mask:0xf
	v_mov_b32_dpp v210, v64 row_ror:1 row_mask:0xf bank_mask:0xf
	v_mov_b32_dpp v211, v65 row_ror:1 row_mask:0xf bank_mask:0xf
	v_mov_b32_dpp v212, v58 row_ror:1 row_mask:0xf bank_mask:0xf
	v_mov_b32_dpp v213, v59 row_ror:1 row_mask:0xf bank_mask:0xf
	v_mov_b32_dpp v214, v60 row_ror:1 row_mask:0xf bank_mask:0xf
	v_mov_b32_dpp v215, v61 row_ror:1 row_mask:0xf bank_mask:0xf
	v_mov_b32_dpp v160, v62 row_ror:2 row_mask:0xf bank_mask:0xf
	v_mov_b32_dpp v161, v63 row_ror:2 row_mask:0xf bank_mask:0xf
	v_mov_b32_dpp v162, v64 row_ror:2 row_mask:0xf bank_mask:0xf
	v_mov_b32_dpp v163, v65 row_ror:2 row_mask:0xf bank_mask:0xf
	v_mov_b32_dpp v164, v58 row_ror:2 row_mask:0xf bank_mask:0xf
	v_mov_b32_dpp v165, v59 row_ror:2 row_mask:0xf bank_mask:0xf
	v_mov_b32_dpp v166, v60 row_ror:2 row_mask:0xf bank_mask:0xf
	v_mov_b32_dpp v167, v61 row_ror:2 row_mask:0xf bank_mask:0xf
	v_cndmask_b32_e64 v192, v192, v208, s[0:1]
	v_cndmask_b32_e64 v193, v193, v209, s[0:1]
	v_cndmask_b32_e64 v194, v194, v210, s[0:1]
	v_cndmask_b32_e64 v195, v195, v211, s[0:1]
	v_cndmask_b32_e64 v196, v196, v212, s[0:1]
	v_cndmask_b32_e64 v197, v197, v213, s[0:1]
	v_cndmask_b32_e64 v198, v198, v214, s[0:1]
	v_cndmask_b32_e64 v199, v199, v215, s[0:1]
	v_cndmask_b32_e64 v200, v200, v160, s[8:9]
	v_cndmask_b32_e64 v201, v201, v161, s[8:9]
	v_cndmask_b32_e64 v202, v202, v162, s[8:9]
	v_cndmask_b32_e64 v203, v203, v163, s[8:9]
	v_cndmask_b32_e64 v204, v204, v164, s[8:9]
	v_cndmask_b32_e64 v205, v205, v165, s[8:9]
	v_cndmask_b32_e64 v206, v206, v166, s[8:9]
	v_cndmask_b32_e64 v207, v207, v167, s[8:9]
	v_mul_f32_e32 v192, v146, v192
	v_mul_f32_e32 v193, v147, v193
	v_mul_f32_e32 v194, v148, v194
	v_mul_f32_e32 v195, v149, v195
	v_mul_f32_e32 v196, v134, v196
	v_mul_f32_e32 v197, v135, v197
	v_mul_f32_e32 v198, v136, v198
	v_mul_f32_e32 v199, v137, v199
	v_mul_f32_e32 v168, v62, v150
	v_mul_f32_e32 v169, v63, v151
	v_mul_f32_e32 v182, v64, v152
	v_mul_f32_e32 v183, v65, v153
	v_mul_f32_e32 v184, v58, v138
	v_mul_f32_e32 v185, v59, v139
	v_mul_f32_e32 v186, v60, v140
	v_mul_f32_e32 v187, v61, v141
	v_fma_f32 v200, v142, v200, v192
	v_fma_f32 v201, v143, v201, v193
	v_fma_f32 v202, v144, v202, v194
	v_fma_f32 v203, v145, v203, v195
	v_fma_f32 v204, v130, v204, v196
	v_fma_f32 v205, v131, v205, v197
	v_fma_f32 v206, v132, v206, v198
	v_fma_f32 v207, v133, v207, v199
	v_add_f32_e32 v168, v168, v200
	v_add_f32_e32 v169, v169, v201
	v_add_f32_e32 v182, v182, v202
	v_add_f32_e32 v183, v183, v203
	v_add_f32_e32 v184, v184, v204
	v_add_f32_e32 v185, v185, v205
	v_add_f32_e32 v186, v186, v206
	v_add_f32_e32 v187, v187, v207
	v_mul_f32_e32 v200, 0xbfb8aa3b, v168
	v_mul_f32_e32 v201, 0xbfb8aa3b, v169
	v_mul_f32_e32 v202, 0xbfb8aa3b, v182
	v_mul_f32_e32 v203, 0xbfb8aa3b, v183
	v_mul_f32_e32 v204, 0xbfb8aa3b, v184
	v_mul_f32_e32 v205, 0xbfb8aa3b, v185
	v_mul_f32_e32 v206, 0xbfb8aa3b, v186
	v_mul_f32_e32 v207, 0xbfb8aa3b, v187
	v_exp_f32_e32 v200, v200
	v_exp_f32_e32 v201, v201
	v_exp_f32_e32 v202, v202
	v_exp_f32_e32 v203, v203
	v_exp_f32_e32 v204, v204
	v_exp_f32_e32 v205, v205
	v_exp_f32_e32 v206, v206
	v_exp_f32_e32 v207, v207
	v_add_f32_e32 v200, 1.0, v200
	v_add_f32_e32 v201, 1.0, v201
	v_add_f32_e32 v202, 1.0, v202
	v_add_f32_e32 v203, 1.0, v203
	v_add_f32_e32 v204, 1.0, v204
	v_add_f32_e32 v205, 1.0, v205
	v_add_f32_e32 v206, 1.0, v206
	v_add_f32_e32 v207, 1.0, v207
	v_rcp_f32_e32 v200, v200
	v_rcp_f32_e32 v201, v201
	v_rcp_f32_e32 v202, v202
	v_rcp_f32_e32 v203, v203
	v_rcp_f32_e32 v204, v204
	v_rcp_f32_e32 v205, v205
	v_rcp_f32_e32 v206, v206
	v_rcp_f32_e32 v207, v207
	v_mul_f32_e32 v168, v168, v200
	v_mul_f32_e32 v169, v169, v201
	v_mul_f32_e32 v182, v182, v202
	v_mul_f32_e32 v183, v183, v203
	v_mul_f32_e32 v184, v184, v204
	v_mul_f32_e32 v185, v185, v205
	v_mul_f32_e32 v186, v186, v206
	v_mul_f32_e32 v187, v187, v207
	v_mul_f32_e32 v168, v30, v168
	v_mul_f32_e32 v169, v31, v169
	v_mul_f32_e32 v182, v32, v182
	v_mul_f32_e32 v183, v33, v183
	v_mul_f32_e32 v184, v26, v184
	v_mul_f32_e32 v185, v27, v185
	v_mul_f32_e32 v186, v28, v186
	v_mul_f32_e32 v187, v29, v187
	v_cvt_pk_bf16_f32 v154, v168, v169
	v_cvt_pk_bf16_f32 v155, v182, v183
	v_cvt_pk_bf16_f32 v156, v184, v185
	v_cvt_pk_bf16_f32 v157, v186, v187
	flat_store_dwordx4 v[158:159], v[154:157]
	v_lshl_add_u64 v[158:159], v[158:159], 0, s[6:7]
	v_mov_b32_dpp v192, v54 row_ror:1 row_mask:0xf bank_mask:0xf
	v_mov_b32_dpp v193, v55 row_ror:1 row_mask:0xf bank_mask:0xf
	v_mov_b32_dpp v194, v56 row_ror:1 row_mask:0xf bank_mask:0xf
	v_mov_b32_dpp v195, v57 row_ror:1 row_mask:0xf bank_mask:0xf
	v_mov_b32_dpp v196, v50 row_ror:1 row_mask:0xf bank_mask:0xf
	v_mov_b32_dpp v197, v51 row_ror:1 row_mask:0xf bank_mask:0xf
	v_mov_b32_dpp v198, v52 row_ror:1 row_mask:0xf bank_mask:0xf
	v_mov_b32_dpp v199, v53 row_ror:1 row_mask:0xf bank_mask:0xf
	v_mov_b32_dpp v200, v54 row_ror:2 row_mask:0xf bank_mask:0xf
	v_mov_b32_dpp v201, v55 row_ror:2 row_mask:0xf bank_mask:0xf
	v_mov_b32_dpp v202, v56 row_ror:2 row_mask:0xf bank_mask:0xf
	v_mov_b32_dpp v203, v57 row_ror:2 row_mask:0xf bank_mask:0xf
	v_mov_b32_dpp v204, v50 row_ror:2 row_mask:0xf bank_mask:0xf
	v_mov_b32_dpp v205, v51 row_ror:2 row_mask:0xf bank_mask:0xf
	v_mov_b32_dpp v206, v52 row_ror:2 row_mask:0xf bank_mask:0xf
	v_mov_b32_dpp v207, v53 row_ror:2 row_mask:0xf bank_mask:0xf
	v_cndmask_b32_e64 v208, v208, v192, s[0:1]
	v_cndmask_b32_e64 v209, v209, v193, s[0:1]
	v_cndmask_b32_e64 v210, v210, v194, s[0:1]
	v_cndmask_b32_e64 v211, v211, v195, s[0:1]
	v_cndmask_b32_e64 v212, v212, v196, s[0:1]
	v_cndmask_b32_e64 v213, v213, v197, s[0:1]
	v_cndmask_b32_e64 v214, v214, v198, s[0:1]
	v_cndmask_b32_e64 v215, v215, v199, s[0:1]
	v_cndmask_b32_e64 v160, v160, v200, s[8:9]
	v_cndmask_b32_e64 v161, v161, v201, s[8:9]
	v_cndmask_b32_e64 v162, v162, v202, s[8:9]
	v_cndmask_b32_e64 v163, v163, v203, s[8:9]
	v_cndmask_b32_e64 v164, v164, v204, s[8:9]
	v_cndmask_b32_e64 v165, v165, v205, s[8:9]
	v_cndmask_b32_e64 v166, v166, v206, s[8:9]
	v_cndmask_b32_e64 v167, v167, v207, s[8:9]
	v_mul_f32_e32 v208, v146, v208
	v_mul_f32_e32 v209, v147, v209
	v_mul_f32_e32 v210, v148, v210
	v_mul_f32_e32 v211, v149, v211
	v_mul_f32_e32 v212, v134, v212
	v_mul_f32_e32 v213, v135, v213
	v_mul_f32_e32 v214, v136, v214
	v_mul_f32_e32 v215, v137, v215
	v_mul_f32_e32 v168, v54, v150
	v_mul_f32_e32 v169, v55, v151
	v_mul_f32_e32 v182, v56, v152
	v_mul_f32_e32 v183, v57, v153
	v_mul_f32_e32 v184, v50, v138
	v_mul_f32_e32 v185, v51, v139
	v_mul_f32_e32 v186, v52, v140
	v_mul_f32_e32 v187, v53, v141
	v_fma_f32 v160, v142, v160, v208
	v_fma_f32 v161, v143, v161, v209
	v_fma_f32 v162, v144, v162, v210
	v_fma_f32 v163, v145, v163, v211
	v_fma_f32 v164, v130, v164, v212
	v_fma_f32 v165, v131, v165, v213
	v_fma_f32 v166, v132, v166, v214
	v_fma_f32 v167, v133, v167, v215
	v_add_f32_e32 v168, v168, v160
	v_add_f32_e32 v169, v169, v161
	v_add_f32_e32 v182, v182, v162
	v_add_f32_e32 v183, v183, v163
	v_add_f32_e32 v184, v184, v164
	v_add_f32_e32 v185, v185, v165
	v_add_f32_e32 v186, v186, v166
	v_add_f32_e32 v187, v187, v167
	v_mul_f32_e32 v160, 0xbfb8aa3b, v168
	v_mul_f32_e32 v161, 0xbfb8aa3b, v169
	v_mul_f32_e32 v162, 0xbfb8aa3b, v182
	v_mul_f32_e32 v163, 0xbfb8aa3b, v183
	v_mul_f32_e32 v164, 0xbfb8aa3b, v184
	v_mul_f32_e32 v165, 0xbfb8aa3b, v185
	v_mul_f32_e32 v166, 0xbfb8aa3b, v186
	v_mul_f32_e32 v167, 0xbfb8aa3b, v187
	v_exp_f32_e32 v160, v160
	v_exp_f32_e32 v161, v161
	v_exp_f32_e32 v162, v162
	v_exp_f32_e32 v163, v163
	v_exp_f32_e32 v164, v164
	v_exp_f32_e32 v165, v165
	v_exp_f32_e32 v166, v166
	v_exp_f32_e32 v167, v167
	v_add_f32_e32 v160, 1.0, v160
	v_add_f32_e32 v161, 1.0, v161
	v_add_f32_e32 v162, 1.0, v162
	v_add_f32_e32 v163, 1.0, v163
	v_add_f32_e32 v164, 1.0, v164
	v_add_f32_e32 v165, 1.0, v165
	v_add_f32_e32 v166, 1.0, v166
	v_add_f32_e32 v167, 1.0, v167
	v_rcp_f32_e32 v160, v160
	v_rcp_f32_e32 v161, v161
	v_rcp_f32_e32 v162, v162
	v_rcp_f32_e32 v163, v163
	v_rcp_f32_e32 v164, v164
	v_rcp_f32_e32 v165, v165
	v_rcp_f32_e32 v166, v166
	v_rcp_f32_e32 v167, v167
	v_mul_f32_e32 v168, v168, v160
	v_mul_f32_e32 v169, v169, v161
	v_mul_f32_e32 v182, v182, v162
	v_mul_f32_e32 v183, v183, v163
	v_mul_f32_e32 v184, v184, v164
	v_mul_f32_e32 v185, v185, v165
	v_mul_f32_e32 v186, v186, v166
	v_mul_f32_e32 v187, v187, v167
	v_mul_f32_e32 v168, v22, v168
	v_mul_f32_e32 v169, v23, v169
	v_mul_f32_e32 v182, v24, v182
	v_mul_f32_e32 v183, v25, v183
	v_mul_f32_e32 v184, v18, v184
	v_mul_f32_e32 v185, v19, v185
	v_mul_f32_e32 v186, v20, v186
	v_mul_f32_e32 v187, v21, v187
	v_cvt_pk_bf16_f32 v154, v168, v169
	v_cvt_pk_bf16_f32 v155, v182, v183
	v_cvt_pk_bf16_f32 v156, v184, v185
	v_cvt_pk_bf16_f32 v157, v186, v187
	flat_store_dwordx4 v[158:159], v[154:157]
	v_lshl_add_u64 v[158:159], v[158:159], 0, s[6:7]
	v_mov_b32_dpp v208, v46 row_ror:1 row_mask:0xf bank_mask:0xf
	v_mov_b32_dpp v209, v47 row_ror:1 row_mask:0xf bank_mask:0xf
	v_mov_b32_dpp v210, v48 row_ror:1 row_mask:0xf bank_mask:0xf
	v_mov_b32_dpp v211, v49 row_ror:1 row_mask:0xf bank_mask:0xf
	v_mov_b32_dpp v212, v42 row_ror:1 row_mask:0xf bank_mask:0xf
	v_mov_b32_dpp v213, v43 row_ror:1 row_mask:0xf bank_mask:0xf
	v_mov_b32_dpp v214, v44 row_ror:1 row_mask:0xf bank_mask:0xf
	v_mov_b32_dpp v215, v45 row_ror:1 row_mask:0xf bank_mask:0xf
	v_mov_b32_dpp v160, v46 row_ror:2 row_mask:0xf bank_mask:0xf
	v_mov_b32_dpp v161, v47 row_ror:2 row_mask:0xf bank_mask:0xf
	v_mov_b32_dpp v162, v48 row_ror:2 row_mask:0xf bank_mask:0xf
	v_mov_b32_dpp v163, v49 row_ror:2 row_mask:0xf bank_mask:0xf
	v_mov_b32_dpp v164, v42 row_ror:2 row_mask:0xf bank_mask:0xf
	v_mov_b32_dpp v165, v43 row_ror:2 row_mask:0xf bank_mask:0xf
	v_mov_b32_dpp v166, v44 row_ror:2 row_mask:0xf bank_mask:0xf
	v_mov_b32_dpp v167, v45 row_ror:2 row_mask:0xf bank_mask:0xf
	v_cndmask_b32_e64 v192, v192, v208, s[0:1]
	v_cndmask_b32_e64 v193, v193, v209, s[0:1]
	v_cndmask_b32_e64 v194, v194, v210, s[0:1]
	v_cndmask_b32_e64 v195, v195, v211, s[0:1]
	v_cndmask_b32_e64 v196, v196, v212, s[0:1]
	v_cndmask_b32_e64 v197, v197, v213, s[0:1]
	v_cndmask_b32_e64 v198, v198, v214, s[0:1]
	v_cndmask_b32_e64 v199, v199, v215, s[0:1]
	v_cndmask_b32_e64 v200, v200, v160, s[8:9]
	v_cndmask_b32_e64 v201, v201, v161, s[8:9]
	v_cndmask_b32_e64 v202, v202, v162, s[8:9]
	v_cndmask_b32_e64 v203, v203, v163, s[8:9]
	v_cndmask_b32_e64 v204, v204, v164, s[8:9]
	v_cndmask_b32_e64 v205, v205, v165, s[8:9]
	v_cndmask_b32_e64 v206, v206, v166, s[8:9]
	v_cndmask_b32_e64 v207, v207, v167, s[8:9]
	v_mul_f32_e32 v192, v146, v192
	v_mul_f32_e32 v193, v147, v193
	v_mul_f32_e32 v194, v148, v194
	v_mul_f32_e32 v195, v149, v195
	v_mul_f32_e32 v196, v134, v196
	v_mul_f32_e32 v197, v135, v197
	v_mul_f32_e32 v198, v136, v198
	v_mul_f32_e32 v199, v137, v199
	v_mul_f32_e32 v168, v46, v150
	v_mul_f32_e32 v169, v47, v151
	v_mul_f32_e32 v182, v48, v152
	v_mul_f32_e32 v183, v49, v153
	v_mul_f32_e32 v184, v42, v138
	v_mul_f32_e32 v185, v43, v139
	v_mul_f32_e32 v186, v44, v140
	v_mul_f32_e32 v187, v45, v141
	v_fma_f32 v200, v142, v200, v192
	v_fma_f32 v201, v143, v201, v193
	v_fma_f32 v202, v144, v202, v194
	v_fma_f32 v203, v145, v203, v195
	v_fma_f32 v204, v130, v204, v196
	v_fma_f32 v205, v131, v205, v197
	v_fma_f32 v206, v132, v206, v198
	v_fma_f32 v207, v133, v207, v199
	v_add_f32_e32 v168, v168, v200
	v_add_f32_e32 v169, v169, v201
	v_add_f32_e32 v182, v182, v202
	v_add_f32_e32 v183, v183, v203
	v_add_f32_e32 v184, v184, v204
	v_add_f32_e32 v185, v185, v205
	v_add_f32_e32 v186, v186, v206
	v_add_f32_e32 v187, v187, v207
	v_mul_f32_e32 v200, 0xbfb8aa3b, v168
	v_mul_f32_e32 v201, 0xbfb8aa3b, v169
	v_mul_f32_e32 v202, 0xbfb8aa3b, v182
	v_mul_f32_e32 v203, 0xbfb8aa3b, v183
	v_mul_f32_e32 v204, 0xbfb8aa3b, v184
	v_mul_f32_e32 v205, 0xbfb8aa3b, v185
	v_mul_f32_e32 v206, 0xbfb8aa3b, v186
	v_mul_f32_e32 v207, 0xbfb8aa3b, v187
	v_exp_f32_e32 v200, v200
	v_exp_f32_e32 v201, v201
	v_exp_f32_e32 v202, v202
	v_exp_f32_e32 v203, v203
	v_exp_f32_e32 v204, v204
	v_exp_f32_e32 v205, v205
	v_exp_f32_e32 v206, v206
	v_exp_f32_e32 v207, v207
	v_add_f32_e32 v200, 1.0, v200
	v_add_f32_e32 v201, 1.0, v201
	v_add_f32_e32 v202, 1.0, v202
	v_add_f32_e32 v203, 1.0, v203
	v_add_f32_e32 v204, 1.0, v204
	v_add_f32_e32 v205, 1.0, v205
	v_add_f32_e32 v206, 1.0, v206
	v_add_f32_e32 v207, 1.0, v207
	v_rcp_f32_e32 v200, v200
	v_rcp_f32_e32 v201, v201
	v_rcp_f32_e32 v202, v202
	v_rcp_f32_e32 v203, v203
	v_rcp_f32_e32 v204, v204
	v_rcp_f32_e32 v205, v205
	v_rcp_f32_e32 v206, v206
	v_rcp_f32_e32 v207, v207
	v_mul_f32_e32 v168, v168, v200
	v_mul_f32_e32 v169, v169, v201
	v_mul_f32_e32 v182, v182, v202
	v_mul_f32_e32 v183, v183, v203
	v_mul_f32_e32 v184, v184, v204
	v_mul_f32_e32 v185, v185, v205
	v_mul_f32_e32 v186, v186, v206
	v_mul_f32_e32 v187, v187, v207
	v_mul_f32_e32 v168, v14, v168
	v_mul_f32_e32 v169, v15, v169
	v_mul_f32_e32 v182, v16, v182
	v_mul_f32_e32 v183, v17, v183
	v_mul_f32_e32 v184, v10, v184
	v_mul_f32_e32 v185, v11, v185
	v_mul_f32_e32 v186, v12, v186
	v_mul_f32_e32 v187, v13, v187
	v_cvt_pk_bf16_f32 v154, v168, v169
	v_cvt_pk_bf16_f32 v155, v182, v183
	v_cvt_pk_bf16_f32 v156, v184, v185
	v_cvt_pk_bf16_f32 v157, v186, v187
	flat_store_dwordx4 v[158:159], v[154:157]
	v_lshl_add_u64 v[158:159], v[158:159], 0, s[6:7]
	v_mov_b32_dpp v192, v38 row_ror:1 row_mask:0xf bank_mask:0xf
	v_mov_b32_dpp v193, v39 row_ror:1 row_mask:0xf bank_mask:0xf
	v_mov_b32_dpp v194, v40 row_ror:1 row_mask:0xf bank_mask:0xf
	v_mov_b32_dpp v195, v41 row_ror:1 row_mask:0xf bank_mask:0xf
	v_mov_b32_dpp v196, v34 row_ror:1 row_mask:0xf bank_mask:0xf
	v_mov_b32_dpp v197, v35 row_ror:1 row_mask:0xf bank_mask:0xf
	v_mov_b32_dpp v198, v36 row_ror:1 row_mask:0xf bank_mask:0xf
	v_mov_b32_dpp v199, v37 row_ror:1 row_mask:0xf bank_mask:0xf
	v_mov_b32_dpp v200, v38 row_ror:2 row_mask:0xf bank_mask:0xf
	v_mov_b32_dpp v201, v39 row_ror:2 row_mask:0xf bank_mask:0xf
	v_mov_b32_dpp v202, v40 row_ror:2 row_mask:0xf bank_mask:0xf
	v_mov_b32_dpp v203, v41 row_ror:2 row_mask:0xf bank_mask:0xf
	v_mov_b32_dpp v204, v34 row_ror:2 row_mask:0xf bank_mask:0xf
	v_mov_b32_dpp v205, v35 row_ror:2 row_mask:0xf bank_mask:0xf
	v_mov_b32_dpp v206, v36 row_ror:2 row_mask:0xf bank_mask:0xf
	v_mov_b32_dpp v207, v37 row_ror:2 row_mask:0xf bank_mask:0xf
	v_cndmask_b32_e64 v208, v208, v192, s[0:1]
	v_cndmask_b32_e64 v209, v209, v193, s[0:1]
	v_cndmask_b32_e64 v210, v210, v194, s[0:1]
	v_cndmask_b32_e64 v211, v211, v195, s[0:1]
	v_cndmask_b32_e64 v212, v212, v196, s[0:1]
	v_cndmask_b32_e64 v213, v213, v197, s[0:1]
	v_cndmask_b32_e64 v214, v214, v198, s[0:1]
	v_cndmask_b32_e64 v215, v215, v199, s[0:1]
	v_cndmask_b32_e64 v160, v160, v200, s[8:9]
	v_cndmask_b32_e64 v161, v161, v201, s[8:9]
	v_cndmask_b32_e64 v162, v162, v202, s[8:9]
	v_cndmask_b32_e64 v163, v163, v203, s[8:9]
	v_cndmask_b32_e64 v164, v164, v204, s[8:9]
	v_cndmask_b32_e64 v165, v165, v205, s[8:9]
	v_cndmask_b32_e64 v166, v166, v206, s[8:9]
	v_cndmask_b32_e64 v167, v167, v207, s[8:9]
	v_mul_f32_e32 v208, v146, v208
	v_mul_f32_e32 v209, v147, v209
	v_mul_f32_e32 v210, v148, v210
	v_mul_f32_e32 v211, v149, v211
	v_mul_f32_e32 v212, v134, v212
	v_mul_f32_e32 v213, v135, v213
	v_mul_f32_e32 v214, v136, v214
	v_mul_f32_e32 v215, v137, v215
	v_mul_f32_e32 v168, v38, v150
	v_mul_f32_e32 v169, v39, v151
	v_mul_f32_e32 v182, v40, v152
	v_mul_f32_e32 v183, v41, v153
	v_mul_f32_e32 v184, v34, v138
	v_mul_f32_e32 v185, v35, v139
	v_mul_f32_e32 v186, v36, v140
	v_mul_f32_e32 v187, v37, v141
	v_fma_f32 v160, v142, v160, v208
	v_fma_f32 v161, v143, v161, v209
	v_fma_f32 v162, v144, v162, v210
	v_fma_f32 v163, v145, v163, v211
	v_fma_f32 v164, v130, v164, v212
	v_fma_f32 v165, v131, v165, v213
	v_fma_f32 v166, v132, v166, v214
	v_fma_f32 v167, v133, v167, v215
	v_add_f32_e32 v168, v168, v160
	v_add_f32_e32 v169, v169, v161
	v_add_f32_e32 v182, v182, v162
	v_add_f32_e32 v183, v183, v163
	v_add_f32_e32 v184, v184, v164
	v_add_f32_e32 v185, v185, v165
	v_add_f32_e32 v186, v186, v166
	v_add_f32_e32 v187, v187, v167
	v_mul_f32_e32 v160, 0xbfb8aa3b, v168
	v_mul_f32_e32 v161, 0xbfb8aa3b, v169
	v_mul_f32_e32 v162, 0xbfb8aa3b, v182
	v_mul_f32_e32 v163, 0xbfb8aa3b, v183
	v_mul_f32_e32 v164, 0xbfb8aa3b, v184
	v_mul_f32_e32 v165, 0xbfb8aa3b, v185
	v_mul_f32_e32 v166, 0xbfb8aa3b, v186
	v_mul_f32_e32 v167, 0xbfb8aa3b, v187
	v_exp_f32_e32 v160, v160
	v_exp_f32_e32 v161, v161
	v_exp_f32_e32 v162, v162
	v_exp_f32_e32 v163, v163
	v_exp_f32_e32 v164, v164
	v_exp_f32_e32 v165, v165
	v_exp_f32_e32 v166, v166
	v_exp_f32_e32 v167, v167
	v_add_f32_e32 v160, 1.0, v160
	v_add_f32_e32 v161, 1.0, v161
	v_add_f32_e32 v162, 1.0, v162
	v_add_f32_e32 v163, 1.0, v163
	v_add_f32_e32 v164, 1.0, v164
	v_add_f32_e32 v165, 1.0, v165
	v_add_f32_e32 v166, 1.0, v166
	v_add_f32_e32 v167, 1.0, v167
	v_rcp_f32_e32 v160, v160
	v_rcp_f32_e32 v161, v161
	v_rcp_f32_e32 v162, v162
	v_rcp_f32_e32 v163, v163
	v_rcp_f32_e32 v164, v164
	v_rcp_f32_e32 v165, v165
	v_rcp_f32_e32 v166, v166
	v_rcp_f32_e32 v167, v167
	v_mul_f32_e32 v168, v168, v160
	v_mul_f32_e32 v169, v169, v161
	v_mul_f32_e32 v182, v182, v162
	v_mul_f32_e32 v183, v183, v163
	v_mul_f32_e32 v184, v184, v164
	v_mul_f32_e32 v185, v185, v165
	v_mul_f32_e32 v186, v186, v166
	v_mul_f32_e32 v187, v187, v167
	v_mul_f32_e32 v168, v6, v168
	v_mul_f32_e32 v169, v7, v169
	v_mul_f32_e32 v182, v8, v182
	v_mul_f32_e32 v183, v9, v183
	v_mul_f32_e32 v184, v2, v184
	v_mul_f32_e32 v185, v3, v185
	v_mul_f32_e32 v186, v4, v186
	v_mul_f32_e32 v187, v5, v187
	v_cvt_pk_bf16_f32 v154, v168, v169
	v_cvt_pk_bf16_f32 v155, v182, v183
	v_cvt_pk_bf16_f32 v156, v184, v185
	v_cvt_pk_bf16_f32 v157, v186, v187
	flat_store_dwordx4 v[158:159], v[154:157]
	s_add_u32 s2, s71, 0xffffff00
	s_addc_u32 s3, s72, -1
	s_andn2_b64 vcc, exec, s[60:61]
	s_cbranch_vccnz .LBB0_337
	s_andn2_b64 vcc, exec, s[28:29]
	s_cbranch_vccnz .LBB0_313
	s_barrier
	s_branch .LBB0_313

.LBB0_1055:
	s_andn2_b64 vcc, exec, s[0:1]
	s_cbranch_vccnz .LBB0_1112
	v_cmp_eq_u32_e32 vcc, 0, v182
	v_cmp_gt_i32_e64 s[6:7], 2, v182
	v_mov_b32_e32 v156, 1.0
	v_cndmask_b32_e64 v0, 1.0, -1.0, vcc
	v_mov_b32_e32 v160, 0
	v_cndmask_b32_e64 v152, 0, v0, s[6:7]
	s_lshl_b32 s78, s70, 8
	v_cndmask_b32_e64 v0, 0, 1, s[22:23]
	v_add_u32_e32 v153, s78, v149
	v_cmp_ne_u32_e64 s[0:1], 1, v0
	s_andn2_b64 vcc, exec, s[22:23]
	v_mov_b32_e32 v161, v160
	v_mov_b32_e32 v162, v160
	v_mov_b32_e32 v163, v160
	v_mov_b32_e32 v170, v160
	v_mov_b32_e32 v171, v160
	v_mov_b32_e32 v168, v160
	v_mov_b32_e32 v169, v160
	v_mov_b32_e32 v157, v156
	v_mov_b32_e32 v158, v156
	v_mov_b32_e32 v159, v156
	v_mov_b32_e32 v164, v156
	v_mov_b32_e32 v165, v156
	v_mov_b32_e32 v166, v156
	v_mov_b32_e32 v167, v156
	s_cbranch_vccnz .LBB0_1058
	v_add_u32_e32 v130, s60, v153
	v_ashrrev_i32_e32 v131, 31, v130
	v_lshlrev_b64 v[130:131], 6, v[130:131]
	v_lshl_add_u64 v[154:155], s[20:21], 0, v[130:131]
	flat_load_dwordx4 v[130:133], v[154:155]
	flat_load_dwordx4 v[134:137], v[154:155] offset:16
	flat_load_dwordx4 v[160:163], v[154:155] offset:32
	flat_load_dwordx4 v[172:175], v[154:155] offset:48
	s_waitcnt vmcnt(0) lgkmcnt(0)
	v_cndmask_b32_e64 v164, 1.0, v130, s[6:7]
	v_cndmask_b32_e64 v156, 1.0, v134, s[6:7]
	v_cndmask_b32_e64 v165, 1.0, v131, s[6:7]
	v_cndmask_b32_e64 v157, 1.0, v135, s[6:7]
	v_cndmask_b32_e64 v166, 1.0, v132, s[6:7]
	v_cndmask_b32_e64 v158, 1.0, v136, s[6:7]
	v_cndmask_b32_e64 v167, 1.0, v133, s[6:7]
	v_cndmask_b32_e64 v159, 1.0, v137, s[6:7]
	v_pk_mul_f32 v[168:169], v[152:153], v[162:163] op_sel_hi:[0,1]
	v_pk_mul_f32 v[170:171], v[152:153], v[160:161] op_sel_hi:[0,1]
	v_pk_mul_f32 v[162:163], v[152:153], v[174:175] op_sel_hi:[0,1]
	v_pk_mul_f32 v[160:161], v[152:153], v[172:173] op_sel_hi:[0,1]
